# loop rotated so the end-of-softmax barrier falls through into the MFMA phase (back-edge branch before the barrier)
# speedup vs baseline: 1.0452x; 1.0007x over previous
; #define ATT_BAR_V(full) do { if (full) { if (MODE) ATT_WAIT_BAR(4); else ATT_WAIT_BAR(2); } else ATT_WAIT_BAR(0); } while (0)
; #define ATT_BAR_L() asm volatile("s_waitcnt lgkmcnt(0)\n\ts_barrier" ::: "memory")
; template <int MODE>
; __device__ __forceinline__ void attn_unit(const Tensors& T0, int ureq, int b, int hh, int qblk, LAS3 char* shm, const bool dummy = false) {
;     ...
;   for (int i = 0; i < NT; ++i) {
;     const int t = t_lo + i;
;     const int k0 = t * 64;
;     float cb = 0.f; bool near = true;
;     if (MODE) { if (k0 + 63 - Q0 <= -91) { cb = cbL; near = false; } else if (k0 - (Q0 + 127) >= 91) { cb = cbR; near = false; } }
;     if (cb != curcb) { curcb = cb;
; #pragma unroll
;       for (int r = 0; r < 16; ++r) negm[r] = cb - mhat; }
;     f32x16 C0 = negm, C1 = negm;
;     if (!(ATT_ABL == 4 && dummy)) { const int kso = (i & 3) * SLOTB; const int vp = ((i - 1) & 3) * SLOTB;
;     ...
;     if (grp == 0) ATT_BAR_V(i + 2 < NT); else if (i + 1 < NT) ATT_BAR_L();
.LBB0_105:
	s_setprio 1
	s_add_i32 s18, s98, 0xffff0000
	s_and_b32 s18, s18, 0x18000
	v_add_u32_e32 v104, s18, v194
	s_add_i32 s97, s98, 0x8000
	s_and_b32 s99, s97, 0x18000
	s_branch .Lm1_head2_g0
.Lm1_bottom_g0:
	s_cmp_ge_u32 s96, s82
	s_cbranch_scc1 .Lm1_B_drain_g0
	s_waitcnt vmcnt(4) lgkmcnt(0)
	s_setprio 1
	s_barrier

; __device__ __forceinline__ unsigned cvtpk(float lo, float hi) { f32x2_t v = {lo, hi}; bf16x2_t b = __builtin_convertvector(v, bf16x2_t); return __builtin_bit_cast(unsigned, b); }
; #define ATT_BAR_V(full) do { if (full) { if (MODE) ATT_WAIT_BAR(4); else ATT_WAIT_BAR(2); } else ATT_WAIT_BAR(0); } while (0)
; #define ATT_BAR_L() asm volatile("s_waitcnt lgkmcnt(0)\n\ts_barrier" ::: "memory")
; template <int MODE>
; __device__ __forceinline__ void attn_unit(const Tensors& T0, int ureq, int b, int hh, int qblk, LAS3 char* shm, const bool dummy = false) {
;     ...
;     float sacc = 0.f;
; #pragma unroll
;     for (int r = 0; r < 16; ++r) { C0[r] = __builtin_amdgcn_exp2f(C0[r]); C1[r] = __builtin_amdgcn_exp2f(C1[r]); sacc += C0[r] + C1[r]; }
;     l_reg += sacc;
; #pragma unroll
;     for (int j = 0; j < 4; ++j) { pw[0][j] = cvtpk(C0[2 * j], C0[2 * j + 1]); pw[1][j] = cvtpk(C0[8 + 2 * j], C0[8 + 2 * j + 1]);
;                                   pw[2][j] = cvtpk(C1[2 * j], C1[2 * j + 1]); pw[3][j] = cvtpk(C1[8 + 2 * j], C1[8 + 2 * j + 1]); }
;     }
;     asm volatile("" : "+v"(pw[0]), "+v"(pw[1]), "+v"(pw[2]), "+v"(pw[3]), "+v"(l_reg));
;     if (grp == 0) ATT_BAR_V(i + 2 < NT); else if (i + 1 < NT) ATT_BAR_L();
.LBB0_125:
	v_exp_f32_e32 v112, v112
	v_exp_f32_e32 v160, v96
	v_exp_f32_e32 v96, v113
	v_exp_f32_e32 v97, v97
	v_exp_f32_e32 v114, v114
	v_exp_f32_e32 v98, v98
	v_exp_f32_e32 v115, v115
	v_exp_f32_e32 v99, v99
	v_add_f32_e32 v113, v160, v112
	v_exp_f32_e32 v116, v116
	v_exp_f32_e32 v100, v100
	v_add_f32_e32 v161, v97, v96
	v_exp_f32_e32 v117, v117
	v_exp_f32_e32 v101, v101
	v_add_f32_e32 v113, v161, v113
	v_add_f32_e32 v161, v98, v114
	v_exp_f32_e32 v118, v118
	v_exp_f32_e32 v102, v102
	v_add_f32_e32 v113, v161, v113
	v_add_f32_e32 v161, v99, v115
	v_exp_f32_e32 v119, v119
	v_exp_f32_e32 v103, v103
	v_add_f32_e32 v113, v161, v113
	v_add_f32_e32 v161, v100, v116
	v_exp_f32_e32 v120, v120
	v_exp_f32_e32 v104, v104
	v_add_f32_e32 v113, v161, v113
	v_add_f32_e32 v161, v101, v117
	v_exp_f32_e32 v121, v121
	v_exp_f32_e32 v105, v105
	v_add_f32_e32 v113, v161, v113
	v_add_f32_e32 v161, v102, v118
	v_exp_f32_e32 v122, v122
	v_exp_f32_e32 v106, v106
	v_add_f32_e32 v113, v161, v113
	v_add_f32_e32 v161, v103, v119
	v_exp_f32_e32 v123, v123
	v_exp_f32_e32 v107, v107
	v_add_f32_e32 v113, v161, v113
	v_add_f32_e32 v161, v104, v120
	v_exp_f32_e32 v124, v124
	v_exp_f32_e32 v108, v108
	v_add_f32_e32 v113, v161, v113
	v_add_f32_e32 v161, v105, v121
	v_exp_f32_e32 v125, v125
	v_exp_f32_e32 v109, v109
	v_add_f32_e32 v113, v161, v113
	v_add_f32_e32 v161, v106, v122
	v_exp_f32_e32 v126, v126
	v_exp_f32_e32 v110, v110
	v_add_f32_e32 v113, v161, v113
	v_add_f32_e32 v161, v107, v123
	v_exp_f32_e32 v127, v127
	v_exp_f32_e32 v111, v111
	v_add_f32_e32 v113, v161, v113
	v_add_f32_e32 v161, v108, v124
	v_add_f32_e32 v113, v161, v113
	v_add_f32_e32 v161, v109, v125
	v_add_f32_e32 v113, v161, v113
	v_add_f32_e32 v161, v110, v126
	v_add_f32_e32 v113, v161, v113
	v_add_f32_e32 v161, v111, v127
	v_add_f32_e32 v113, v161, v113
	v_cvt_pk_bf16_f32 v96, v112, v96
	v_cvt_pk_bf16_f32 v168, v120, v121
	v_cvt_pk_bf16_f32 v164, v160, v97
	v_cvt_pk_bf16_f32 v160, v104, v105
	v_cvt_pk_bf16_f32 v97, v114, v115
	v_cvt_pk_bf16_f32 v169, v122, v123
	v_cvt_pk_bf16_f32 v165, v98, v99
	v_cvt_pk_bf16_f32 v161, v106, v107
	v_cvt_pk_bf16_f32 v98, v116, v117
	v_cvt_pk_bf16_f32 v170, v124, v125
	v_cvt_pk_bf16_f32 v166, v100, v101
	v_cvt_pk_bf16_f32 v162, v108, v109
	v_cvt_pk_bf16_f32 v99, v118, v119
	v_cvt_pk_bf16_f32 v171, v126, v127
	v_cvt_pk_bf16_f32 v167, v102, v103
	v_cvt_pk_bf16_f32 v163, v110, v111
	v_add_f32_e32 v198, v198, v113
	s_add_i32 s93, s93, 1
	s_add_i32 s8, s94, s93
	s_add_i32 s95, s95, 64
	s_add_u32 s100, s100, s68
	s_addc_u32 s101, s101, s69
	v_add_u32_e32 v203, 0x100, v203
	s_mov_b32 s98, s97
	s_add_i32 s18, s98, 0xffff0000
	s_and_b32 s18, s18, 0x18000
	v_add_u32_e32 v104, s18, v194
	s_add_i32 s97, s98, 0x8000
	s_and_b32 s99, s97, 0x18000
	s_branch .Lm1_bottom_g0

; #define ATT_BAR_V(full) do { if (full) { if (MODE) ATT_WAIT_BAR(4); else ATT_WAIT_BAR(2); } else ATT_WAIT_BAR(0); } while (0)
; #define ATT_BAR_L() asm volatile("s_waitcnt lgkmcnt(0)\n\ts_barrier" ::: "memory")
; template <int MODE>
; __device__ __forceinline__ void attn_unit(const Tensors& T0, int ureq, int b, int hh, int qblk, LAS3 char* shm, const bool dummy = false) {
;     ...
;     if (grp == 0) ATT_BAR_V(i + 2 < NT); else if (i + 1 < NT) ATT_BAR_L();
.Lm1_bottom_g1:
	s_cmp_ge_u32 s96, s83
	s_cbranch_scc1 .LBB0_136
	s_waitcnt lgkmcnt(0)
	s_setprio 1
	s_barrier
